# v16 plus next-phase weight tiles prefetched into L2 by waves 1-7 while the barrier completes
# baseline (speedup 1.0000x reference)
; __device__ __forceinline__ void xcd_barrier(const XcdBarrier& b) {
;     asm volatile("s_waitcnt vmcnt(0)" ::: "memory");
;     __syncthreads();
;     if (threadIdx.x == 0) {
;         unsigned* bar = b.bar;
;         __builtin_amdgcn_s_waitcnt(0);
;         unsigned nloc = b.st[0], nx = b.st[1];
;         if (nloc == 0u) { xcd_barrier_complete(bar, b.x, nloc, nx); b.st[0] = nloc; b.st[1] = nx; }
; __global__ void __launch_bounds__(NWAVES * 64, 2) fwd_megakernel(Args args) {
;     ...
;         if (d.kind != K_FINAL) xcd_barrier(bar);
.LBB0_475:
	s_load_dword s0, s[14:15], 0x70
	v_readlane_b32 s20, v254, 62
	v_readlane_b32 s21, v254, 63
	s_waitcnt lgkmcnt(0)
	s_cmp_eq_u32 s0, 7
	s_cbranch_scc1 .LBB0_64
	s_waitcnt vmcnt(0)
	s_waitcnt vmcnt(0)
	s_barrier
	v_readlane_b32 s0, v255, 20
	s_nop 3
	s_cmp_eq_u32 s0, 0
	s_cbranch_scc1 .Lpf_skip
	s_load_dwordx4 s[0:3], s[14:15], 0xc0
	s_load_dwordx2 s[6:7], s[14:15], 0xd8
	v_lshrrev_b32_e32 v0, 6, v228
	v_and_b32_e32 v2, 63, v228
	v_lshrrev_b32_e32 v1, 2, v0
	v_and_b32_e32 v3, 3, v0
	v_lshlrev_b32_e32 v3, 13, v3
	v_lshlrev_b32_e32 v2, 7, v2
	s_waitcnt lgkmcnt(0)
	s_add_i32 s1, s0, -3
	s_cmp_gt_u32 s1, 2
	s_cbranch_scc1 .Lpf_skip
	s_lshr_b32 s1, s72, 3
	s_cmp_eq_u32 s0, 3
	s_cbranch_scc0 .Lpf_fwd
	s_lshr_b32 s0, s2, 4
	s_sub_i32 s1, s0, s1
	s_add_i32 s1, s1, -1
.Lpf_fwd:
	s_lshr_b32 s0, s2, 5
	s_cmp_ge_u32 s1, s0
	s_cselect_b32 s0, s0, 0
	s_sub_i32 s1, s1, s0
	s_lshr_b32 s1, s1, 3
	s_mul_i32 s1, s1, s3
	s_lshl_b32 s1, s1, 9
	s_add_u32 s6, s6, s1
	s_addc_u32 s7, s7, 0
	s_lshl_b32 s1, s3, 8
	v_mul_lo_u32 v1, v1, s1
	v_readfirstlane_b32 s0, v0
	v_add3_u32 v3, v3, v1, v2
	s_nop 3
	s_cmp_eq_u32 s0, 0
	s_cbranch_scc1 .Lpf_skip
	global_load_dword v2, v3, s[6:7]
	s_cmp_eq_u32 s0, 1
	s_cbranch_scc0 .Lpf_skip
	v_subrev_u32_e32 v3, 0x2000, v3
	global_load_dword v1, v3, s[6:7]
.Lpf_skip:
	s_and_saveexec_b64 s[4:5], s[82:83]
	s_cbranch_execz .LBB0_63
	s_and_b32 s0, s88, 0xff
	s_mul_i32 s0, s0, 27
	s_lshr_b32 s0, s0, 9
	s_mul_i32 s0, s0, 19
	s_sub_i32 s0, s88, s0
	s_lshr_b32 s0, 0, s0
	s_andn2_b32 s0, 1, s0
	v_readlane_b32 s1, v255, 20
	s_cmp_lg_u32 s1, 0
	s_cselect_b32 s0, s0, 0
	v_writelane_b32 v255, s0, 26
	v_readlane_b32 s0, v254, 53
	s_waitcnt vmcnt(0) expcnt(0) lgkmcnt(0)
	s_nop 0
	v_mov_b32_e32 v0, s0
	ds_read_b32 v2, v0
	v_readlane_b32 s0, v254, 54
	s_waitcnt lgkmcnt(0)
	v_cmp_ne_u32_e32 vcc, 0, v2
	v_mov_b32_e32 v0, s0
	ds_read_b32 v0, v0
	s_cbranch_vccnz .LBB0_492
	s_mov_b32 s0, 1
	s_branch .LBB0_480
